# P6 x1 and P9 out stores sc0 sc1 nt
# speedup vs baseline: 1.0022x; 1.0001x over previous
; __device__ __forceinline__ float bf_lo(unsigned w) { return __uint_as_float(w << 16); }
; __device__ __forceinline__ float bf_hi(unsigned w) { return __uint_as_float(w & 0xffff0000u); }
; #define GAS __attribute__((address_space(1)))
; __global__ void __launch_bounds__(NWAVES * 64) mega_fwd(Args args) {
;     ...
;         const int b = row >> 11; const float* mb = MOD + (size_t)b * NMOD;
;         GAS f32x4* zr = (GAS f32x4*)(out + (size_t)row * D) + lane;
;         const GAS f32x4* xr = (const GAS f32x4*)(x + (size_t)row * D) + lane;
;         const GAS unsigned long long* yr = (const GAS unsigned long long*)(Y1 + (size_t)row * D) + lane;
;         f32x4 v[4]; float s = 0.f;
; #pragma unroll
;         for (int j = 0; j < 4; ++j) { const f32x4 xv = __builtin_nontemporal_load(&xr[64 * j]); const unsigned long long yy = __builtin_nontemporal_load(&yr[64 * j]); const unsigned ylo = (unsigned)yy, yhi = (unsigned)(yy >> 32);
;             v[j] = xv * ALPHA + (f32x4){pg8::bf_lo(ylo), pg8::bf_hi(ylo), pg8::bf_lo(yhi), pg8::bf_hi(yhi)};
;             s += (v[j].x + v[j].y) + (v[j].z + v[j].w); }
;         float mean = wave_sum(s, lane) * (1.f / D), s2 = 0.f;
; #pragma unroll
;         for (int j = 0; j < 4; ++j) { v[j] = v[j] - mean; s2 += (v[j].x * v[j].x + v[j].y * v[j].y) + (v[j].z * v[j].z + v[j].w * v[j].w); }
;         float rstd = 1.f / sqrtf(wave_sum(s2, lane) * (1.f / D) + LN_EPS);
.LBB0_543:
	global_load_dwordx2 v[32:33], v[38:39], off offset:-1536 nt
	global_load_dwordx2 v[34:35], v[38:39], off offset:-1024 nt
	global_load_dwordx2 v[46:47], v[38:39], off offset:-512 nt
	global_load_dwordx2 v[48:49], v[38:39], off nt
	v_lshl_add_u64 v[50:51], s[10:11], 0, v[36:37]
	global_load_dwordx4 v[62:65], v[50:51], off nt
	global_load_dwordx4 v[66:69], v[50:51], off offset:1024 nt
	global_load_dwordx4 v[70:73], v[50:51], off offset:2048 nt
	global_load_dwordx4 v[74:77], v[50:51], off offset:3072 nt
	s_ashr_i32 s0, s13, 11
	s_mul_hi_i32 s1, s0, 0x6000
	s_mulk_i32 s0, 0x6000
	s_add_u32 s0, s28, s0
	v_add_co_u32_e32 v44, vcc, s35, v38
	s_addc_u32 s1, s29, s1
	s_nop 0
	v_addc_co_u32_e32 v45, vcc, -1, v39, vcc
	v_lshl_add_u64 v[78:79], s[0:1], 0, v[40:41]
	v_lshl_add_u64 v[50:51], v[78:79], 0, s[14:15]
	v_lshl_add_u64 v[52:53], v[78:79], 0, s[16:17]
	v_add_co_u32_e32 v78, vcc, s30, v78
	v_lshl_add_u64 v[42:43], s[2:3], 0, v[36:37]
	s_nop 0
	v_addc_co_u32_e32 v79, vcc, 0, v79, vcc
	v_lshl_add_u64 v[38:39], v[38:39], 0, s[8:9]
	s_waitcnt vmcnt(7)
	v_lshlrev_b32_e32 v80, 16, v32
	v_and_b32_e32 v81, 0xffff0000, v32
	v_lshlrev_b32_e32 v32, 16, v33
	v_and_b32_e32 v33, 0xffff0000, v33
	s_waitcnt vmcnt(6)
	v_lshlrev_b32_e32 v82, 16, v34
	v_and_b32_e32 v83, 0xffff0000, v34
	v_lshlrev_b32_e32 v34, 16, v35
	v_and_b32_e32 v35, 0xffff0000, v35
	s_waitcnt vmcnt(5)
	v_lshlrev_b32_e32 v84, 16, v46
	v_and_b32_e32 v85, 0xffff0000, v46
	v_lshlrev_b32_e32 v46, 16, v47
	v_and_b32_e32 v47, 0xffff0000, v47
	s_waitcnt vmcnt(4)
	v_lshlrev_b32_e32 v86, 16, v48
	v_and_b32_e32 v87, 0xffff0000, v48
	v_lshlrev_b32_e32 v48, 16, v49
	v_and_b32_e32 v49, 0xffff0000, v49
	s_waitcnt vmcnt(3)
	v_pk_fma_f32 v[32:33], v[64:65], s[12:13], v[32:33] op_sel_hi:[1,0,1]
	v_pk_fma_f32 v[62:63], v[62:63], s[12:13], v[80:81] op_sel_hi:[1,0,1]
	s_waitcnt vmcnt(2)
	v_pk_fma_f32 v[34:35], v[68:69], s[12:13], v[34:35] op_sel_hi:[1,0,1]
	v_pk_fma_f32 v[64:65], v[66:67], s[12:13], v[82:83] op_sel_hi:[1,0,1]
	s_waitcnt vmcnt(1)
	v_pk_fma_f32 v[46:47], v[72:73], s[12:13], v[46:47] op_sel_hi:[1,0,1]
	v_pk_fma_f32 v[66:67], v[70:71], s[12:13], v[84:85] op_sel_hi:[1,0,1]
	s_waitcnt vmcnt(0)
	v_pk_fma_f32 v[48:49], v[76:77], s[12:13], v[48:49] op_sel_hi:[1,0,1]
	v_pk_fma_f32 v[68:69], v[74:75], s[12:13], v[86:87] op_sel_hi:[1,0,1]
	v_pk_mov_b32 v[70:71], v[62:63], v[32:33] op_sel:[1,0]
	v_mov_b32_e32 v72, v62
	v_mov_b32_e32 v73, v33
	v_pk_mov_b32 v[74:75], v[64:65], v[34:35] op_sel:[1,0]
	v_mov_b32_e32 v76, v64
	v_mov_b32_e32 v77, v35
	v_pk_add_f32 v[70:71], v[70:71], v[72:73]
	v_pk_add_f32 v[72:73], v[74:75], v[76:77]
	v_add_f32_e32 v76, v70, v71
	v_pk_add_f32 v[70:71], v[72:73], v[72:73] op_sel:[0,1] op_sel_hi:[1,0]
	v_add_f32_e32 v80, v66, v67
	v_add_f32_e32 v82, v46, v47
	v_mov_b32_e32 v85, v68
	v_mov_b32_e32 v81, v48
	v_mov_b32_e32 v83, v49
	v_add_f32_e32 v84, 0, v76
	v_mov_b32_e32 v71, v69
	v_pk_add_f32 v[74:75], v[80:81], v[82:83]
	v_pk_add_f32 v[70:71], v[84:85], v[70:71]
	s_add_i32 s13, s13, s34
	v_pk_add_f32 v[70:71], v[70:71], v[74:75]
	s_add_u32 s2, s2, s6
	v_add_f32_e32 v70, v70, v71
	s_addc_u32 s3, s3, s7
	s_add_u32 s10, s10, s6
	s_addc_u32 s11, s11, s7
	s_cmp_gt_i32 s13, 0xffff
	s_waitcnt lgkmcnt(0)
	s_nop 1
	v_add_f32_dpp v70, v70, v70 quad_perm:[1,0,3,2] row_mask:0xf bank_mask:0xf
	s_waitcnt lgkmcnt(0)
	s_nop 1
	v_add_f32_dpp v70, v70, v70 quad_perm:[2,3,0,1] row_mask:0xf bank_mask:0xf
	s_waitcnt lgkmcnt(0)
	s_nop 1
	v_add_f32_dpp v70, v70, v70 row_half_mirror row_mask:0xf bank_mask:0xf
	s_waitcnt lgkmcnt(0)
	s_nop 1
	v_add_f32_dpp v70, v70, v70 row_mirror row_mask:0xf bank_mask:0xf
	s_waitcnt lgkmcnt(0)
	v_mov_b32_e32 v71, v70
	s_nop 1
	v_permlane16_swap_b32_e32 v70, v71
	v_add_f32_e32 v70, v70, v71
	s_waitcnt lgkmcnt(0)
	v_mov_b32_e32 v71, v70
	s_nop 1
	v_permlane32_swap_b32_e32 v70, v71
	v_add_f32_e32 v70, v70, v71
	v_fmamk_f32 v63, v70, 0xba800000, v63
	v_fmac_f32_e32 v62, 0xba800000, v70
	v_fmamk_f32 v33, v70, 0xba800000, v33
	v_fmac_f32_e32 v32, 0xba800000, v70
	v_fmamk_f32 v65, v70, 0xba800000, v65
	v_fmac_f32_e32 v64, 0xba800000, v70
	v_fmamk_f32 v35, v70, 0xba800000, v35
	v_fmac_f32_e32 v34, 0xba800000, v70
	v_fmamk_f32 v67, v70, 0xba800000, v67
	v_fmac_f32_e32 v66, 0xba800000, v70
	v_fmamk_f32 v47, v70, 0xba800000, v47
	v_fmac_f32_e32 v46, 0xba800000, v70
	v_fmamk_f32 v49, v70, 0xba800000, v49
	v_fmac_f32_e32 v48, 0xba800000, v70
	v_fmamk_f32 v69, v70, 0xba800000, v69
	v_fmac_f32_e32 v68, 0xba800000, v70
	v_pk_mul_f32 v[70:71], v[32:33], v[32:33]
	v_pk_mul_f32 v[72:73], v[62:63], v[62:63]
	v_pk_mul_f32 v[74:75], v[34:35], v[34:35]
	v_pk_mul_f32 v[76:77], v[64:65], v[64:65]
	v_pk_mov_b32 v[84:85], v[72:73], v[70:71] op_sel:[1,0]
	v_mov_b32_e32 v73, v71
	v_pk_mov_b32 v[70:71], v[76:77], v[74:75] op_sel:[1,0]
	v_mov_b32_e32 v77, v75
	v_mul_f32_e32 v83, v68, v68
	v_mul_f32_e32 v80, v67, v67
	v_mul_f32_e32 v82, v47, v47
	v_pk_add_f32 v[72:73], v[84:85], v[72:73]
	v_pk_add_f32 v[70:71], v[70:71], v[76:77]
	v_mul_f32_e32 v86, v69, v69
	v_mul_f32_e32 v87, v48, v48
	v_mul_f32_e32 v88, v49, v49
	v_pk_fma_f32 v[74:75], v[66:67], v[66:67], v[80:81] op_sel_hi:[1,1,0]
	v_pk_fma_f32 v[80:81], v[46:47], v[46:47], v[82:83] op_sel_hi:[1,1,0]
	v_pk_add_f32 v[72:73], v[72:73], v[72:73] op_sel:[0,1] op_sel_hi:[1,0]
	v_pk_add_f32 v[70:71], v[70:71], v[70:71] op_sel:[0,1] op_sel_hi:[1,0]
	v_mov_b32_e32 v75, v87
	v_mov_b32_e32 v81, v88
	v_mov_b32_e32 v73, v83
	v_mov_b32_e32 v71, v86
	v_pk_add_f32 v[74:75], v[74:75], v[80:81]
	v_pk_add_f32 v[70:71], v[72:73], v[70:71]
	s_nop 0
	v_pk_add_f32 v[70:71], v[70:71], v[74:75]
	s_nop 0
	v_add_f32_e32 v70, v70, v71
	s_waitcnt lgkmcnt(0)
; #define GAS __attribute__((address_space(1)))
; __global__ void __launch_bounds__(NWAVES * 64) mega_fwd(Args args) {
;     ...
;         float rstd = 1.f / sqrtf(wave_sum(s2, lane) * (1.f / D) + LN_EPS);
;         s = 0.f;
; #pragma unroll
;         for (int j = 0; j < 4; ++j) { const f32x4 gg = g1v[j], bb = b1v[j];
;             v[j] = v[j] * rstd * gg + bb; __builtin_nontemporal_store(v[j], &zr[64 * j]); s += (v[j].x + v[j].y) + (v[j].z + v[j].w); }
;         mean = wave_sum(s, lane) * (1.f / D); s2 = 0.f;
; #pragma unroll
;         for (int j = 0; j < 4; ++j) { v[j] = v[j] - mean; s2 += (v[j].x * v[j].x + v[j].y * v[j].y) + (v[j].z * v[j].z + v[j].w * v[j].w); }
;         rstd = 1.f / sqrtf(wave_sum(s2, lane) * (1.f / D) + LN_EPS);
;         GAS unsigned long long* o8 = (GAS unsigned long long*)(HB + (size_t)row * D) + lane;
	s_nop 1
	v_add_f32_dpp v70, v70, v70 quad_perm:[1,0,3,2] row_mask:0xf bank_mask:0xf
	s_waitcnt lgkmcnt(0)
	s_nop 1
	v_add_f32_dpp v70, v70, v70 quad_perm:[2,3,0,1] row_mask:0xf bank_mask:0xf
	s_waitcnt lgkmcnt(0)
	s_nop 1
	v_add_f32_dpp v70, v70, v70 row_half_mirror row_mask:0xf bank_mask:0xf
	s_waitcnt lgkmcnt(0)
	s_nop 1
	v_add_f32_dpp v70, v70, v70 row_mirror row_mask:0xf bank_mask:0xf
	s_waitcnt lgkmcnt(0)
	v_mov_b32_e32 v71, v70
	s_nop 1
	v_permlane16_swap_b32_e32 v70, v71
	v_add_f32_e32 v70, v70, v71
	s_waitcnt lgkmcnt(0)
	v_mov_b32_e32 v71, v70
	s_nop 1
	v_permlane32_swap_b32_e32 v70, v71
	v_add_f32_e32 v70, v70, v71
	v_fmamk_f32 v70, v70, 0x3a800000, v60
	v_mul_f32_e32 v71, 0x4f800000, v70
	v_cmp_gt_f32_e32 vcc, s23, v70
	s_nop 1
	v_cndmask_b32_e32 v70, v70, v71, vcc
	v_sqrt_f32_e32 v71, v70
	s_nop 0
	v_add_u32_e32 v72, -1, v71
	v_add_u32_e32 v73, 1, v71
	v_fma_f32 v74, -v72, v71, v70
	v_fma_f32 v75, -v73, v71, v70
	v_cmp_ge_f32_e64 s[0:1], 0, v74
	s_nop 1
	v_cndmask_b32_e64 v71, v71, v72, s[0:1]
	v_cmp_lt_f32_e64 s[0:1], 0, v75
	s_nop 1
	v_cndmask_b32_e64 v71, v71, v73, s[0:1]
	v_mul_f32_e32 v72, 0x37800000, v71
	v_cndmask_b32_e32 v71, v71, v72, vcc
	v_cmp_class_f32_e32 vcc, v70, v61
	s_nop 1
	v_cndmask_b32_e32 v70, v71, v70, vcc
	v_div_scale_f32 v71, s[0:1], v70, v70, 1.0
	v_rcp_f32_e32 v73, v71
	v_div_scale_f32 v72, vcc, 1.0, v70, 1.0
	v_fma_f32 v74, -v71, v73, 1.0
	v_fmac_f32_e32 v73, v74, v73
	v_mul_f32_e32 v74, v72, v73
	v_fma_f32 v75, -v71, v74, v72
	v_fmac_f32_e32 v74, v75, v73
	v_fma_f32 v71, -v71, v74, v72
	v_div_fmas_f32 v71, v71, v73, v74
	v_div_fixup_f32 v70, v71, v70, 1.0
	v_pk_mul_f32 v[32:33], v[70:71], v[32:33] op_sel_hi:[0,1]
	v_pk_mul_f32 v[62:63], v[70:71], v[62:63] op_sel_hi:[0,1]
	v_pk_mul_f32 v[34:35], v[70:71], v[34:35] op_sel_hi:[0,1]
	v_pk_mul_f32 v[64:65], v[70:71], v[64:65] op_sel_hi:[0,1]
	v_pk_mul_f32 v[72:73], v[70:71], v[46:47] op_sel_hi:[0,1]
	v_pk_mul_f32 v[66:67], v[70:71], v[66:67] op_sel_hi:[0,1]
	v_pk_mul_f32 v[74:75], v[70:71], v[68:69] op_sel_hi:[0,1]
	v_pk_mul_f32 v[70:71], v[70:71], v[48:49] op_sel_hi:[0,1]
	v_pk_fma_f32 v[46:47], v[62:63], v[0:1], v[4:5]
	v_pk_fma_f32 v[48:49], v[32:33], v[2:3], v[6:7]
	v_pk_fma_f32 v[62:63], v[64:65], v[8:9], v[12:13]
	v_pk_fma_f32 v[64:65], v[34:35], v[10:11], v[14:15]
	v_pk_fma_f32 v[66:67], v[66:67], v[16:17], v[20:21]
	v_pk_fma_f32 v[68:69], v[72:73], v[18:19], v[22:23]
	v_pk_fma_f32 v[34:35], v[70:71], v[26:27], v[30:31]
	v_pk_fma_f32 v[32:33], v[74:75], v[24:25], v[28:29]
	v_pk_mov_b32 v[70:71], v[46:47], v[48:49] op_sel:[1,0]
	v_mov_b32_e32 v72, v46
	v_mov_b32_e32 v73, v49
	v_pk_mov_b32 v[74:75], v[62:63], v[64:65] op_sel:[1,0]
	v_mov_b32_e32 v76, v62
	v_mov_b32_e32 v77, v65
	global_store_dwordx4 v[42:43], v[46:49], off sc0 sc1 nt
	global_store_dwordx4 v[42:43], v[62:65], off offset:1024 sc0 sc1 nt
	global_store_dwordx4 v[42:43], v[66:69], off offset:2048 sc0 sc1 nt
	global_store_dwordx4 v[42:43], v[32:35], off offset:3072 sc0 sc1 nt
	v_pk_add_f32 v[84:85], v[70:71], v[72:73]
	v_pk_add_f32 v[86:87], v[74:75], v[76:77]
	global_load_dwordx4 v[70:73], v[78:79], off offset:-4096
	global_load_dwordx4 v[74:77], v[78:79], off
	v_add_f32_e32 v42, v84, v85
	v_pk_add_f32 v[78:79], v[86:87], v[86:87] op_sel:[0,1] op_sel_hi:[1,0]
	v_add_f32_e32 v80, v66, v67
	v_add_f32_e32 v82, v68, v69
	v_mov_b32_e32 v43, v32
	v_mov_b32_e32 v81, v34
	v_mov_b32_e32 v83, v35
	v_add_f32_e32 v42, 0, v42
	v_mov_b32_e32 v79, v33
	v_pk_add_f32 v[80:81], v[80:81], v[82:83]
	v_pk_add_f32 v[42:43], v[42:43], v[78:79]
	s_waitcnt vmcnt(0)
	v_pk_add_f32 v[74:75], v[74:75], 1.0 op_sel_hi:[1,0]
	v_pk_add_f32 v[42:43], v[42:43], v[80:81]
	s_nop 0
	v_add_f32_e32 v42, v42, v43
	s_waitcnt lgkmcnt(0)
	s_nop 1
	v_add_f32_dpp v42, v42, v42 quad_perm:[1,0,3,2] row_mask:0xf bank_mask:0xf
	s_waitcnt lgkmcnt(0)
	s_nop 1
	v_add_f32_dpp v42, v42, v42 quad_perm:[2,3,0,1] row_mask:0xf bank_mask:0xf
	s_waitcnt lgkmcnt(0)
	s_nop 1
	v_add_f32_dpp v42, v42, v42 row_half_mirror row_mask:0xf bank_mask:0xf
	s_waitcnt lgkmcnt(0)
	s_nop 1
	v_add_f32_dpp v42, v42, v42 row_mirror row_mask:0xf bank_mask:0xf
	s_waitcnt lgkmcnt(0)
	v_mov_b32_e32 v43, v42
	s_nop 1
	v_permlane16_swap_b32_e32 v42, v43
	v_add_f32_e32 v42, v42, v43
	s_waitcnt lgkmcnt(0)
	v_mov_b32_e32 v43, v42
	s_nop 1
	v_permlane32_swap_b32_e32 v42, v43
	v_add_f32_e32 v42, v42, v43
	v_fmamk_f32 v47, v42, 0xba800000, v47
	v_fmac_f32_e32 v46, 0xba800000, v42
	v_fmamk_f32 v49, v42, 0xba800000, v49
	v_fmac_f32_e32 v48, 0xba800000, v42
	v_fmamk_f32 v63, v42, 0xba800000, v63
	v_fmac_f32_e32 v62, 0xba800000, v42
	v_fmamk_f32 v65, v42, 0xba800000, v65
	v_fmac_f32_e32 v64, 0xba800000, v42
	v_fmamk_f32 v67, v42, 0xba800000, v67
	v_fmac_f32_e32 v66, 0xba800000, v42
	v_fmamk_f32 v69, v42, 0xba800000, v69
	v_fmac_f32_e32 v68, 0xba800000, v42
	v_fmamk_f32 v35, v42, 0xba800000, v35
	v_fmac_f32_e32 v34, 0xba800000, v42
	v_fmamk_f32 v33, v42, 0xba800000, v33
	v_fmac_f32_e32 v32, 0xba800000, v42
	v_pk_mul_f32 v[42:43], v[48:49], v[48:49]
	v_pk_mul_f32 v[78:79], v[46:47], v[46:47]
	v_pk_mul_f32 v[80:81], v[64:65], v[64:65]
	v_pk_mul_f32 v[82:83], v[62:63], v[62:63]
	v_pk_mov_b32 v[88:89], v[78:79], v[42:43] op_sel:[1,0]
	v_mov_b32_e32 v79, v43
	v_pk_mov_b32 v[42:43], v[82:83], v[80:81] op_sel:[1,0]
	v_mov_b32_e32 v83, v81
	v_mul_f32_e32 v87, v32, v32
	v_mul_f32_e32 v84, v67, v67
	v_mul_f32_e32 v86, v69, v69
	v_pk_add_f32 v[78:79], v[88:89], v[78:79]
	v_pk_add_f32 v[42:43], v[42:43], v[82:83]
	v_mul_f32_e32 v90, v33, v33
	v_mul_f32_e32 v91, v34, v34
	v_mul_f32_e32 v92, v35, v35
	v_pk_fma_f32 v[80:81], v[66:67], v[66:67], v[84:85] op_sel_hi:[1,1,0]
	v_pk_fma_f32 v[84:85], v[68:69], v[68:69], v[86:87] op_sel_hi:[1,1,0]
	v_pk_add_f32 v[78:79], v[78:79], v[78:79] op_sel:[0,1] op_sel_hi:[1,0]
	v_pk_add_f32 v[42:43], v[42:43], v[42:43] op_sel:[0,1] op_sel_hi:[1,0]
	v_mov_b32_e32 v81, v91
	v_mov_b32_e32 v85, v92
	v_mov_b32_e32 v79, v87
	v_mov_b32_e32 v43, v90
	v_pk_add_f32 v[80:81], v[80:81], v[84:85]
	v_pk_add_f32 v[42:43], v[78:79], v[42:43]
	s_nop 0
	v_pk_add_f32 v[42:43], v[42:43], v[80:81]
	s_nop 0
	v_add_f32_e32 v42, v42, v43
	s_waitcnt lgkmcnt(0)
; #define GAS __attribute__((address_space(1)))
; __device__ __forceinline__ unsigned pk2(float lo, float hi) { return f2bf(lo) | (f2bf(hi) << 16); }
; __global__ void __launch_bounds__(NWAVES * 64) mega_fwd(Args args) {
;     ...
;         rstd = 1.f / sqrtf(wave_sum(s2, lane) * (1.f / D) + LN_EPS);
;         GAS unsigned long long* o8 = (GAS unsigned long long*)(HB + (size_t)row * D) + lane;
; #pragma unroll
;         for (int j = 0; j < 4; ++j) { const f32x4 sh = *(const f32x4*)(mb + 3072 + 256 * j + 4 * lane), sc = *(const f32x4*)(mb + 4096 + 256 * j + 4 * lane);
;             const f32x4 y = v[j] * rstd * (sc + 1.0f) + sh;
;             o8[64 * j] = (unsigned long long)pk2(y.x, y.y) | ((unsigned long long)pk2(y.z, y.w) << 32); }
	s_nop 1
	v_add_f32_dpp v42, v42, v42 quad_perm:[1,0,3,2] row_mask:0xf bank_mask:0xf
	s_waitcnt lgkmcnt(0)
	s_nop 1
	v_add_f32_dpp v42, v42, v42 quad_perm:[2,3,0,1] row_mask:0xf bank_mask:0xf
	s_waitcnt lgkmcnt(0)
	s_nop 1
	v_add_f32_dpp v42, v42, v42 row_half_mirror row_mask:0xf bank_mask:0xf
	s_waitcnt lgkmcnt(0)
	s_nop 1
	v_add_f32_dpp v42, v42, v42 row_mirror row_mask:0xf bank_mask:0xf
	s_waitcnt lgkmcnt(0)
	v_mov_b32_e32 v43, v42
	v_mov_b32_e32 v78, v42
	s_nop 1
	v_permlane16_swap_b32_e32 v78, v43
	v_add_f32_e32 v78, v78, v43
	v_pk_add_f32 v[42:43], v[76:77], 1.0 op_sel_hi:[1,0]
	s_waitcnt lgkmcnt(0)
	v_mov_b32_e32 v76, v78
	s_nop 1
	v_permlane32_swap_b32_e32 v78, v76
	v_add_f32_e32 v76, v78, v76
	v_fmamk_f32 v76, v76, 0x3a800000, v60
	v_mul_f32_e32 v77, 0x4f800000, v76
	v_cmp_gt_f32_e32 vcc, s23, v76
	s_nop 1
	v_cndmask_b32_e32 v76, v76, v77, vcc
	v_sqrt_f32_e32 v77, v76
	s_nop 0
	v_add_u32_e32 v78, -1, v77
	v_add_u32_e32 v79, 1, v77
	v_fma_f32 v80, -v78, v77, v76
	v_fma_f32 v81, -v79, v77, v76
	v_cmp_ge_f32_e64 s[0:1], 0, v80
	s_nop 1
	v_cndmask_b32_e64 v77, v77, v78, s[0:1]
	v_cmp_lt_f32_e64 s[0:1], 0, v81
	s_nop 1
	v_cndmask_b32_e64 v77, v77, v79, s[0:1]
	v_mul_f32_e32 v78, 0x37800000, v77
	v_cndmask_b32_e32 v77, v77, v78, vcc
	v_cmp_class_f32_e32 vcc, v76, v61
	s_nop 1
	v_cndmask_b32_e32 v76, v77, v76, vcc
	v_div_scale_f32 v77, s[0:1], v76, v76, 1.0
	v_rcp_f32_e32 v79, v77
	v_div_scale_f32 v78, vcc, 1.0, v76, 1.0
	v_fma_f32 v80, -v77, v79, 1.0
	v_fmac_f32_e32 v79, v80, v79
	v_mul_f32_e32 v80, v78, v79
	v_fma_f32 v81, -v77, v80, v78
	v_fmac_f32_e32 v80, v81, v79
	v_fma_f32 v77, -v77, v80, v78
	v_div_fmas_f32 v77, v77, v79, v80
	v_div_fixup_f32 v76, v77, v76, 1.0
	v_pk_mul_f32 v[46:47], v[76:77], v[46:47] op_sel_hi:[0,1]
	v_pk_mul_f32 v[48:49], v[76:77], v[48:49] op_sel_hi:[0,1]
	v_pk_fma_f32 v[42:43], v[48:49], v[42:43], v[72:73]
	v_pk_fma_f32 v[46:47], v[46:47], v[74:75], v[70:71]
	v_bfe_u32 v70, v42, 16, 1
	v_bfe_u32 v48, v46, 16, 1
	v_bfe_u32 v49, v47, 16, 1
	v_bfe_u32 v71, v43, 16, 1
	v_add3_u32 v46, v46, v48, s31
	v_add3_u32 v42, v42, v70, s31
	v_add3_u32 v47, v47, v49, s31
	v_add3_u32 v43, v43, v71, s31
	v_lshrrev_b32_e32 v46, 16, v46
	v_lshrrev_b32_e32 v48, 16, v42
	v_and_or_b32 v42, v47, s22, v46
	v_and_or_b32 v43, v43, s22, v48
	global_store_dwordx2 v[44:45], v[42:43], off offset:-1536
	global_load_dwordx4 v[46:49], v[52:53], off offset:1024
	global_load_dwordx4 v[70:73], v[50:51], off offset:1024
	v_pk_mul_f32 v[42:43], v[76:77], v[62:63] op_sel_hi:[0,1]
	v_pk_mul_f32 v[62:63], v[76:77], v[64:65] op_sel_hi:[0,1]
	v_pk_mul_f32 v[32:33], v[76:77], v[32:33] op_sel_hi:[0,1]
	v_pk_mul_f32 v[34:35], v[76:77], v[34:35] op_sel_hi:[0,1]
	s_waitcnt vmcnt(1)
	v_pk_add_f32 v[48:49], v[48:49], 1.0 op_sel_hi:[1,0]
	v_pk_add_f32 v[46:47], v[46:47], 1.0 op_sel_hi:[1,0]
	s_waitcnt vmcnt(0)
	v_pk_fma_f32 v[48:49], v[62:63], v[48:49], v[72:73]
	v_pk_fma_f32 v[42:43], v[42:43], v[46:47], v[70:71]
	v_bfe_u32 v62, v48, 16, 1
	v_bfe_u32 v46, v42, 16, 1
	v_bfe_u32 v47, v43, 16, 1
	v_bfe_u32 v63, v49, 16, 1
	v_add3_u32 v42, v42, v46, s31
	v_add3_u32 v46, v48, v62, s31
	v_add3_u32 v43, v43, v47, s31
	v_add3_u32 v47, v49, v63, s31
	v_lshrrev_b32_e32 v42, 16, v42
	v_lshrrev_b32_e32 v46, 16, v46
	v_and_or_b32 v42, v43, s22, v42
	v_and_or_b32 v43, v47, s22, v46
	global_store_dwordx2 v[44:45], v[42:43], off offset:-1024
	global_load_dwordx4 v[46:49], v[52:53], off offset:2048
	global_load_dwordx4 v[62:65], v[50:51], off offset:2048
	v_pk_mul_f32 v[42:43], v[76:77], v[66:67] op_sel_hi:[0,1]
	v_pk_mul_f32 v[66:67], v[76:77], v[68:69] op_sel_hi:[0,1]
	s_waitcnt vmcnt(1)
	v_pk_add_f32 v[48:49], v[48:49], 1.0 op_sel_hi:[1,0]
	v_pk_add_f32 v[46:47], v[46:47], 1.0 op_sel_hi:[1,0]
	s_waitcnt vmcnt(0)
	v_pk_fma_f32 v[48:49], v[66:67], v[48:49], v[64:65]
	v_pk_fma_f32 v[42:43], v[42:43], v[46:47], v[62:63]
	v_bfe_u32 v62, v48, 16, 1
	v_bfe_u32 v46, v42, 16, 1
	v_bfe_u32 v47, v43, 16, 1
	v_bfe_u32 v63, v49, 16, 1
	v_add3_u32 v42, v42, v46, s31
	v_add3_u32 v46, v48, v62, s31
	v_add3_u32 v43, v43, v47, s31
	v_add3_u32 v47, v49, v63, s31
	v_lshrrev_b32_e32 v42, 16, v42
	v_lshrrev_b32_e32 v46, 16, v46
	v_and_or_b32 v42, v43, s22, v42
	v_and_or_b32 v43, v47, s22, v46
	global_store_dwordx2 v[44:45], v[42:43], off offset:-512
	global_load_dwordx4 v[46:49], v[52:53], off offset:3072
	s_nop 0
	global_load_dwordx4 v[50:53], v[50:51], off offset:3072
	s_waitcnt vmcnt(1)
	v_pk_add_f32 v[42:43], v[48:49], 1.0 op_sel_hi:[1,0]
	v_pk_add_f32 v[46:47], v[46:47], 1.0 op_sel_hi:[1,0]
	s_waitcnt vmcnt(0)
	v_pk_fma_f32 v[34:35], v[34:35], v[42:43], v[52:53]
	v_pk_fma_f32 v[32:33], v[32:33], v[46:47], v[50:51]
	v_bfe_u32 v46, v34, 16, 1
	v_bfe_u32 v42, v32, 16, 1
	v_bfe_u32 v43, v33, 16, 1
	v_bfe_u32 v47, v35, 16, 1
	v_add3_u32 v32, v32, v42, s31
	v_add3_u32 v34, v34, v46, s31
	v_add3_u32 v33, v33, v43, s31
	v_add3_u32 v35, v35, v47, s31
	v_lshrrev_b32_e32 v32, 16, v32
	v_lshrrev_b32_e32 v34, 16, v34
	v_and_or_b32 v32, v33, s22, v32
	v_and_or_b32 v33, v35, s22, v34
	global_store_dwordx2 v[44:45], v[32:33], off
	s_cbranch_scc0 .LBB0_543

; __device__ __forceinline__ float bf_lo(unsigned w) { return __uint_as_float(w << 16); }
; __device__ __forceinline__ float bf_hi(unsigned w) { return __uint_as_float(w & 0xffff0000u); }
; #define GAS __attribute__((address_space(1)))
; __global__ void __launch_bounds__(NWAVES * 64) mega_fwd(Args args) {
;     ...
;     for (int row = gw; row < MROWS; row += NGW) {
;         GAS f32x4* zr = (GAS f32x4*)(out + (size_t)row * D) + lane;
;         const GAS unsigned long long* yr = (const GAS unsigned long long*)(Y2 + (size_t)row * D) + lane;
;         f32x4 v[4]; float s = 0.f;
; #pragma unroll
;         for (int j = 0; j < 4; ++j) { const f32x4 xv = __builtin_nontemporal_load(&zr[64 * j]); const unsigned long long yy = __builtin_nontemporal_load(&yr[64 * j]); const unsigned ylo = (unsigned)yy, yhi = (unsigned)(yy >> 32);
;             v[j] = xv * ALPHA + (f32x4){pg8::bf_lo(ylo), pg8::bf_hi(ylo), pg8::bf_lo(yhi), pg8::bf_hi(yhi)};
;             s += (v[j].x + v[j].y) + (v[j].z + v[j].w); }
;         const float mean = wave_sum(s, lane) * (1.f / D); float s2 = 0.f;
.LBB0_746:
	global_load_dwordx2 v[40:41], v[34:35], off offset:-1024 nt
	global_load_dwordx2 v[46:47], v[34:35], off offset:-512 nt
	global_load_dwordx2 v[64:65], v[34:35], off nt
	global_load_dwordx2 v[66:67], v[34:35], off offset:512 nt
	global_load_dwordx4 v[36:39], v[32:33], off offset:-3072 nt
	global_load_dwordx4 v[42:45], v[32:33], off offset:-2048 nt
	global_load_dwordx4 v[48:51], v[32:33], off offset:-1024 nt
	global_load_dwordx4 v[60:63], v[32:33], off nt
	v_lshl_add_u64 v[34:35], v[34:35], 0, s[4:5]
	s_waitcnt vmcnt(7)
	v_lshlrev_b32_e32 v68, 16, v40
	v_and_b32_e32 v69, 0xffff0000, v40
	v_lshlrev_b32_e32 v40, 16, v41
	v_and_b32_e32 v41, 0xffff0000, v41
	s_waitcnt vmcnt(6)
	v_lshlrev_b32_e32 v70, 16, v46
	v_and_b32_e32 v71, 0xffff0000, v46
	v_lshlrev_b32_e32 v72, 16, v47
	v_and_b32_e32 v73, 0xffff0000, v47
	s_waitcnt vmcnt(5)
	v_lshlrev_b32_e32 v74, 16, v64
	v_and_b32_e32 v75, 0xffff0000, v64
	v_lshlrev_b32_e32 v64, 16, v65
	v_and_b32_e32 v65, 0xffff0000, v65
	s_waitcnt vmcnt(4)
	v_lshlrev_b32_e32 v76, 16, v66
	v_and_b32_e32 v77, 0xffff0000, v66
	v_lshlrev_b32_e32 v66, 16, v67
	v_and_b32_e32 v67, 0xffff0000, v67
	s_waitcnt vmcnt(3)
	v_pk_fma_f32 v[40:41], v[38:39], s[6:7], v[40:41] op_sel_hi:[1,0,1]
	v_pk_fma_f32 v[46:47], v[36:37], s[6:7], v[68:69] op_sel_hi:[1,0,1]
	s_waitcnt vmcnt(2)
	v_pk_fma_f32 v[38:39], v[44:45], s[6:7], v[72:73] op_sel_hi:[1,0,1]
	v_pk_fma_f32 v[44:45], v[42:43], s[6:7], v[70:71] op_sel_hi:[1,0,1]
	s_waitcnt vmcnt(1)
	v_pk_fma_f32 v[36:37], v[50:51], s[6:7], v[64:65] op_sel_hi:[1,0,1]
	v_pk_fma_f32 v[42:43], v[48:49], s[6:7], v[74:75] op_sel_hi:[1,0,1]
	s_waitcnt vmcnt(0)
	v_pk_fma_f32 v[48:49], v[62:63], s[6:7], v[66:67] op_sel_hi:[1,0,1]
	v_pk_fma_f32 v[50:51], v[60:61], s[6:7], v[76:77] op_sel_hi:[1,0,1]
	v_pk_mov_b32 v[60:61], v[46:47], v[40:41] op_sel:[1,0]
	v_mov_b32_e32 v62, v46
	v_mov_b32_e32 v63, v41
	v_pk_mov_b32 v[64:65], v[44:45], v[38:39] op_sel:[1,0]
	v_mov_b32_e32 v66, v44
	v_mov_b32_e32 v67, v39
	v_pk_add_f32 v[60:61], v[60:61], v[62:63]
	v_pk_add_f32 v[62:63], v[64:65], v[66:67]
	v_add_f32_e32 v66, v60, v61
	v_pk_add_f32 v[60:61], v[62:63], v[62:63] op_sel:[0,1] op_sel_hi:[1,0]
	v_add_f32_e32 v68, v42, v43
	v_add_f32_e32 v70, v36, v37
	v_mov_b32_e32 v73, v50
	v_mov_b32_e32 v69, v48
	v_mov_b32_e32 v71, v49
	v_add_f32_e32 v72, 0, v66
	v_mov_b32_e32 v61, v51
	v_pk_add_f32 v[64:65], v[68:69], v[70:71]
	v_pk_add_f32 v[60:61], v[72:73], v[60:61]
	s_add_i32 s7, s7, s34
	v_pk_add_f32 v[60:61], v[60:61], v[64:65]
	s_cmp_gt_i32 s7, 0xffff
	v_add_f32_e32 v60, v60, v61
	s_waitcnt lgkmcnt(0)
	s_nop 1
	v_add_f32_dpp v60, v60, v60 quad_perm:[1,0,3,2] row_mask:0xf bank_mask:0xf
	s_waitcnt lgkmcnt(0)
	s_nop 1
	v_add_f32_dpp v60, v60, v60 quad_perm:[2,3,0,1] row_mask:0xf bank_mask:0xf
	s_waitcnt lgkmcnt(0)
	s_nop 1
	v_add_f32_dpp v60, v60, v60 row_half_mirror row_mask:0xf bank_mask:0xf
	s_waitcnt lgkmcnt(0)
	s_nop 1
	v_add_f32_dpp v60, v60, v60 row_mirror row_mask:0xf bank_mask:0xf
	s_waitcnt lgkmcnt(0)
	v_mov_b32_e32 v61, v60
	s_nop 1
	v_permlane16_swap_b32_e32 v60, v61
	v_add_f32_e32 v60, v60, v61
	s_waitcnt lgkmcnt(0)
; __global__ void __launch_bounds__(NWAVES * 64) mega_fwd(Args args) {
;     ...
;         const float mean = wave_sum(s, lane) * (1.f / D); float s2 = 0.f;
; #pragma unroll
;         for (int j = 0; j < 4; ++j) { v[j] = v[j] - mean; s2 += (v[j].x * v[j].x + v[j].y * v[j].y) + (v[j].z * v[j].z + v[j].w * v[j].w); }
;         const float rstd = 1.f / sqrtf(wave_sum(s2, lane) * (1.f / D) + LN_EPS);
; #pragma unroll
;         for (int j = 0; j < 4; ++j) { const f32x4 gg = g2v[j], bb = b2v[j];
;             __builtin_nontemporal_store(v[j] * rstd * gg + bb, &zr[64 * j]); }
	v_mov_b32_e32 v61, v60
	s_nop 1
	v_permlane32_swap_b32_e32 v60, v61
	v_add_f32_e32 v60, v60, v61
	v_fmamk_f32 v47, v60, 0xba800000, v47
	v_fmac_f32_e32 v46, 0xba800000, v60
	v_fmamk_f32 v41, v60, 0xba800000, v41
	v_fmac_f32_e32 v40, 0xba800000, v60
	v_fmamk_f32 v45, v60, 0xba800000, v45
	v_fmac_f32_e32 v44, 0xba800000, v60
	v_fmamk_f32 v39, v60, 0xba800000, v39
	v_fmac_f32_e32 v38, 0xba800000, v60
	v_fmamk_f32 v43, v60, 0xba800000, v43
	v_fmac_f32_e32 v42, 0xba800000, v60
	v_fmamk_f32 v37, v60, 0xba800000, v37
	v_fmac_f32_e32 v36, 0xba800000, v60
	v_fmamk_f32 v49, v60, 0xba800000, v49
	v_fmac_f32_e32 v48, 0xba800000, v60
	v_fmamk_f32 v51, v60, 0xba800000, v51
	v_fmac_f32_e32 v50, 0xba800000, v60
	v_pk_mul_f32 v[60:61], v[40:41], v[40:41]
	v_pk_mul_f32 v[62:63], v[46:47], v[46:47]
	v_pk_mul_f32 v[64:65], v[38:39], v[38:39]
	v_pk_mul_f32 v[66:67], v[44:45], v[44:45]
	v_pk_mov_b32 v[72:73], v[62:63], v[60:61] op_sel:[1,0]
	v_mov_b32_e32 v63, v61
	v_pk_mov_b32 v[60:61], v[66:67], v[64:65] op_sel:[1,0]
	v_mov_b32_e32 v67, v65
	v_mul_f32_e32 v71, v50, v50
	v_mul_f32_e32 v68, v43, v43
	v_mul_f32_e32 v70, v37, v37
	v_pk_add_f32 v[62:63], v[72:73], v[62:63]
	v_pk_add_f32 v[60:61], v[60:61], v[66:67]
	v_mul_f32_e32 v74, v51, v51
	v_mul_f32_e32 v75, v48, v48
	v_mul_f32_e32 v76, v49, v49
	v_pk_fma_f32 v[64:65], v[42:43], v[42:43], v[68:69] op_sel_hi:[1,1,0]
	v_pk_fma_f32 v[68:69], v[36:37], v[36:37], v[70:71] op_sel_hi:[1,1,0]
	v_pk_add_f32 v[62:63], v[62:63], v[62:63] op_sel:[0,1] op_sel_hi:[1,0]
	v_pk_add_f32 v[60:61], v[60:61], v[60:61] op_sel:[0,1] op_sel_hi:[1,0]
	v_mov_b32_e32 v65, v75
	v_mov_b32_e32 v69, v76
	v_mov_b32_e32 v63, v71
	v_mov_b32_e32 v61, v74
	v_pk_add_f32 v[64:65], v[64:65], v[68:69]
	v_pk_add_f32 v[60:61], v[62:63], v[60:61]
	s_nop 0
	v_pk_add_f32 v[60:61], v[60:61], v[64:65]
	s_nop 0
	v_add_f32_e32 v60, v60, v61
	s_waitcnt lgkmcnt(0)
	s_nop 1
	v_add_f32_dpp v60, v60, v60 quad_perm:[1,0,3,2] row_mask:0xf bank_mask:0xf
	s_waitcnt lgkmcnt(0)
	s_nop 1
	v_add_f32_dpp v60, v60, v60 quad_perm:[2,3,0,1] row_mask:0xf bank_mask:0xf
	s_waitcnt lgkmcnt(0)
	s_nop 1
	v_add_f32_dpp v60, v60, v60 row_half_mirror row_mask:0xf bank_mask:0xf
	s_waitcnt lgkmcnt(0)
	s_nop 1
	v_add_f32_dpp v60, v60, v60 row_mirror row_mask:0xf bank_mask:0xf
	s_waitcnt lgkmcnt(0)
	v_mov_b32_e32 v61, v60
	s_nop 1
	v_permlane16_swap_b32_e32 v60, v61
	v_add_f32_e32 v60, v60, v61
	s_waitcnt lgkmcnt(0)
	v_mov_b32_e32 v61, v60
	s_nop 1
	v_permlane32_swap_b32_e32 v60, v61
	v_add_f32_e32 v60, v60, v61
	v_fmamk_f32 v60, v60, 0x3a800000, v58
	v_mul_f32_e32 v61, 0x4f800000, v60
	v_cmp_gt_f32_e32 vcc, s8, v60
	s_nop 1
	v_cndmask_b32_e32 v60, v60, v61, vcc
	v_sqrt_f32_e32 v61, v60
	s_nop 0
	v_add_u32_e32 v62, -1, v61
	v_add_u32_e32 v63, 1, v61
	v_fma_f32 v64, -v62, v61, v60
	v_fma_f32 v65, -v63, v61, v60
	v_cmp_ge_f32_e64 s[0:1], 0, v64
	s_nop 1
	v_cndmask_b32_e64 v61, v61, v62, s[0:1]
	v_cmp_lt_f32_e64 s[0:1], 0, v65
	s_nop 1
	v_cndmask_b32_e64 v61, v61, v63, s[0:1]
	v_mul_f32_e32 v62, 0x37800000, v61
	v_cndmask_b32_e32 v61, v61, v62, vcc
	v_cmp_class_f32_e32 vcc, v60, v59
	s_nop 1
	v_cndmask_b32_e32 v60, v61, v60, vcc
	v_div_scale_f32 v61, s[0:1], v60, v60, 1.0
	v_rcp_f32_e32 v62, v61
	v_div_scale_f32 v63, vcc, 1.0, v60, 1.0
	v_fma_f32 v64, -v61, v62, 1.0
	v_fmac_f32_e32 v62, v64, v62
	v_mul_f32_e32 v64, v63, v62
	v_fma_f32 v65, -v61, v64, v63
	v_fmac_f32_e32 v64, v65, v62
	v_fma_f32 v61, -v61, v64, v63
	v_div_fmas_f32 v61, v61, v62, v64
	v_div_fixup_f32 v60, v61, v60, 1.0
	v_pk_mul_f32 v[46:47], v[60:61], v[46:47] op_sel_hi:[0,1]
	v_pk_mul_f32 v[40:41], v[60:61], v[40:41] op_sel_hi:[0,1]
	v_pk_mul_f32 v[44:45], v[60:61], v[44:45] op_sel_hi:[0,1]
	v_pk_mul_f32 v[62:63], v[60:61], v[38:39] op_sel_hi:[0,1]
	v_pk_mul_f32 v[64:65], v[60:61], v[42:43] op_sel_hi:[0,1]
	v_pk_mul_f32 v[66:67], v[60:61], v[36:37] op_sel_hi:[0,1]
	v_pk_mul_f32 v[68:69], v[60:61], v[50:51] op_sel_hi:[0,1]
	v_pk_mul_f32 v[48:49], v[60:61], v[48:49] op_sel_hi:[0,1]
	v_pk_fma_f32 v[38:39], v[40:41], v[2:3], v[6:7]
	v_pk_fma_f32 v[36:37], v[46:47], v[0:1], v[4:5]
	v_pk_fma_f32 v[42:43], v[62:63], v[10:11], v[14:15]
	v_pk_fma_f32 v[40:41], v[44:45], v[8:9], v[12:13]
	v_pk_fma_f32 v[46:47], v[66:67], v[18:19], v[22:23]
	v_pk_fma_f32 v[44:45], v[64:65], v[16:17], v[20:21]
	v_pk_fma_f32 v[50:51], v[48:49], v[26:27], v[30:31]
	v_pk_fma_f32 v[48:49], v[68:69], v[24:25], v[28:29]
	global_store_dwordx4 v[32:33], v[36:39], off offset:-3072 sc0 sc1 nt
	global_store_dwordx4 v[32:33], v[40:43], off offset:-2048 sc0 sc1 nt
	global_store_dwordx4 v[32:33], v[44:47], off offset:-1024 sc0 sc1 nt
	global_store_dwordx4 v[32:33], v[48:51], off sc0 sc1 nt
	v_lshl_add_u64 v[32:33], v[32:33], 0, s[2:3]
	s_cbranch_scc0 .LBB0_746
